# PEER stage B: two pieces converted together, their pk_fma chains interleaved (no dependent back-to-back pk ops)
# baseline (speedup 1.0000x reference)
.Lpb_unit:
	s_lshl_b32 s0, s17, 11
	s_add_i32 s0, s0, s27
	s_cmp_eq_u32 s17, 8
	s_cselect_b32 s0, s44, s0
	s_lshl_b32 s1, s16, 9
	s_lshl_b32 s24, s0, 12
	s_add_u32 s24, s24, s1
	s_add_u32 s20, s4, s24
	s_addc_u32 s21, s5, 0
	s_add_u32 s36, s6, s1
	s_addc_u32 s37, s7, 0
	s_lshl_b32 s25, s16, 21
	s_add_u32 s18, s8, s25
	s_addc_u32 s19, s9, 0
	s_lshl_b32 s25, s17, 9
	v_add_u32_e32 v205, s25, v190
	v_add_u32_e32 v210, s25, v209
	s_lshl_b32 s25, s17, 2
	v_add_u32_e32 v206, s25, v204
	ds_read_b128 v[64:67], v205
	ds_read_b128 v[68:71], v205 offset:16
	ds_read_b128 v[72:75], v205 offset:32
	ds_read_b128 v[76:79], v205 offset:48
	ds_read_b32 v208, v206
	global_load_dwordx4 v[80:83], v189, s[20:21]
	global_load_dwordx4 v[84:87], v189, s[20:21] offset:16
	global_load_dwordx4 v[88:91], v189, s[20:21] offset:32
	global_load_dwordx4 v[92:95], v189, s[20:21] offset:48
	s_waitcnt lgkmcnt(1)
	v_add_u32_e32 v64, v64, v188
	v_add_u32_e32 v65, v65, v188
	v_add_u32_e32 v66, v66, v188
	v_add_u32_e32 v67, v67, v188
	v_add_u32_e32 v68, v68, v188
	v_add_u32_e32 v69, v69, v188
	v_add_u32_e32 v70, v70, v188
	v_add_u32_e32 v71, v71, v188
	v_add_u32_e32 v72, v72, v188
	v_add_u32_e32 v73, v73, v188
	v_add_u32_e32 v74, v74, v188
	v_add_u32_e32 v75, v75, v188
	v_add_u32_e32 v76, v76, v188
	v_add_u32_e32 v77, v77, v188
	v_add_u32_e32 v78, v78, v188
	v_add_u32_e32 v79, v79, v188
	global_load_dwordx4 v[0:3], v64, s[18:19]
	global_load_dwordx4 v[4:7], v65, s[18:19]
	global_load_dwordx4 v[8:11], v66, s[18:19]
	global_load_dwordx4 v[12:15], v67, s[18:19]
	global_load_dwordx4 v[16:19], v68, s[18:19]
	global_load_dwordx4 v[20:23], v69, s[18:19]
	global_load_dwordx4 v[24:27], v70, s[18:19]
	global_load_dwordx4 v[28:31], v71, s[18:19]
	global_load_dwordx4 v[32:35], v72, s[18:19]
	global_load_dwordx4 v[36:39], v73, s[18:19]
	global_load_dwordx4 v[40:43], v74, s[18:19]
	global_load_dwordx4 v[44:47], v75, s[18:19]
	global_load_dwordx4 v[48:51], v76, s[18:19]
	global_load_dwordx4 v[52:55], v77, s[18:19]
	global_load_dwordx4 v[56:59], v78, s[18:19]
	global_load_dwordx4 v[60:63], v79, s[18:19]
	s_waitcnt vmcnt(16) lgkmcnt(0)
	v_pk_mul_f32 v[80:81], v[80:81], v[128:129]
	v_pk_mul_f32 v[82:83], v[82:83], v[130:131]
	v_pk_mul_f32 v[84:85], v[84:85], v[132:133]
	v_pk_mul_f32 v[86:87], v[86:87], v[134:135]
	v_pk_mul_f32 v[88:89], v[88:89], v[136:137]
	v_pk_mul_f32 v[90:91], v[90:91], v[138:139]
	v_pk_mul_f32 v[92:93], v[92:93], v[140:141]
	v_pk_mul_f32 v[94:95], v[94:95], v[142:143]
	s_waitcnt vmcnt(15)
	v_cvt_pk_f32_fp8_e32 v[168:169], v0
	v_cvt_pk_f32_fp8_sdwa v[170:171], v0 src0_sel:WORD_1
	v_cvt_pk_f32_fp8_e32 v[172:173], v1
	v_cvt_pk_f32_fp8_sdwa v[174:175], v1 src0_sel:WORD_1
	v_cvt_pk_f32_fp8_e32 v[176:177], v2
	v_cvt_pk_f32_fp8_sdwa v[178:179], v2 src0_sel:WORD_1
	v_cvt_pk_f32_fp8_e32 v[180:181], v3
	v_cvt_pk_f32_fp8_sdwa v[182:183], v3 src0_sel:WORD_1
	s_waitcnt vmcnt(14)
	v_cvt_pk_f32_fp8_e32 v[96:97], v4
	v_cvt_pk_f32_fp8_sdwa v[98:99], v4 src0_sel:WORD_1
	v_cvt_pk_f32_fp8_e32 v[100:101], v5
	v_cvt_pk_f32_fp8_sdwa v[102:103], v5 src0_sel:WORD_1
	v_cvt_pk_f32_fp8_e32 v[104:105], v6
	v_cvt_pk_f32_fp8_sdwa v[106:107], v6 src0_sel:WORD_1
	v_cvt_pk_f32_fp8_e32 v[108:109], v7
	v_cvt_pk_f32_fp8_sdwa v[110:111], v7 src0_sel:WORD_1
	v_pk_mul_f32 v[184:185], v[168:169], v[80:81]
	v_pk_mul_f32 v[186:187], v[96:97], v[80:81]
	v_pk_fma_f32 v[184:185], v[170:171], v[82:83], v[184:185]
	v_pk_fma_f32 v[186:187], v[98:99], v[82:83], v[186:187]
	v_pk_fma_f32 v[184:185], v[172:173], v[84:85], v[184:185]
	v_pk_fma_f32 v[186:187], v[100:101], v[84:85], v[186:187]
	v_pk_fma_f32 v[184:185], v[174:175], v[86:87], v[184:185]
	v_pk_fma_f32 v[186:187], v[102:103], v[86:87], v[186:187]
	v_pk_fma_f32 v[184:185], v[176:177], v[88:89], v[184:185]
	v_pk_fma_f32 v[186:187], v[104:105], v[88:89], v[186:187]
	v_pk_fma_f32 v[184:185], v[178:179], v[90:91], v[184:185]
	v_pk_fma_f32 v[186:187], v[106:107], v[90:91], v[186:187]
	v_pk_fma_f32 v[184:185], v[180:181], v[92:93], v[184:185]
	v_pk_fma_f32 v[186:187], v[108:109], v[92:93], v[186:187]
	v_pk_fma_f32 v[184:185], v[182:183], v[94:95], v[184:185]
	v_pk_fma_f32 v[186:187], v[110:111], v[94:95], v[186:187]
	v_add_f32_e32 v112, v184, v185
	v_add_f32_e32 v113, v186, v187
	s_waitcnt vmcnt(13)
	v_cvt_pk_f32_fp8_e32 v[168:169], v8
	v_cvt_pk_f32_fp8_sdwa v[170:171], v8 src0_sel:WORD_1
	v_cvt_pk_f32_fp8_e32 v[172:173], v9
	v_cvt_pk_f32_fp8_sdwa v[174:175], v9 src0_sel:WORD_1
	v_cvt_pk_f32_fp8_e32 v[176:177], v10
	v_cvt_pk_f32_fp8_sdwa v[178:179], v10 src0_sel:WORD_1
	v_cvt_pk_f32_fp8_e32 v[180:181], v11
	v_cvt_pk_f32_fp8_sdwa v[182:183], v11 src0_sel:WORD_1
	s_waitcnt vmcnt(12)
	v_cvt_pk_f32_fp8_e32 v[96:97], v12
	v_cvt_pk_f32_fp8_sdwa v[98:99], v12 src0_sel:WORD_1
	v_cvt_pk_f32_fp8_e32 v[100:101], v13
	v_cvt_pk_f32_fp8_sdwa v[102:103], v13 src0_sel:WORD_1
	v_cvt_pk_f32_fp8_e32 v[104:105], v14
	v_cvt_pk_f32_fp8_sdwa v[106:107], v14 src0_sel:WORD_1
	v_cvt_pk_f32_fp8_e32 v[108:109], v15
	v_cvt_pk_f32_fp8_sdwa v[110:111], v15 src0_sel:WORD_1
	v_pk_mul_f32 v[184:185], v[168:169], v[80:81]
	v_pk_mul_f32 v[186:187], v[96:97], v[80:81]
	v_pk_fma_f32 v[184:185], v[170:171], v[82:83], v[184:185]
	v_pk_fma_f32 v[186:187], v[98:99], v[82:83], v[186:187]
	v_pk_fma_f32 v[184:185], v[172:173], v[84:85], v[184:185]
	v_pk_fma_f32 v[186:187], v[100:101], v[84:85], v[186:187]
	v_pk_fma_f32 v[184:185], v[174:175], v[86:87], v[184:185]
	v_pk_fma_f32 v[186:187], v[102:103], v[86:87], v[186:187]
	v_pk_fma_f32 v[184:185], v[176:177], v[88:89], v[184:185]
	v_pk_fma_f32 v[186:187], v[104:105], v[88:89], v[186:187]
	v_pk_fma_f32 v[184:185], v[178:179], v[90:91], v[184:185]
	v_pk_fma_f32 v[186:187], v[106:107], v[90:91], v[186:187]
	v_pk_fma_f32 v[184:185], v[180:181], v[92:93], v[184:185]
	v_pk_fma_f32 v[186:187], v[108:109], v[92:93], v[186:187]
	v_pk_fma_f32 v[184:185], v[182:183], v[94:95], v[184:185]
	v_pk_fma_f32 v[186:187], v[110:111], v[94:95], v[186:187]
	v_add_f32_e32 v114, v184, v185
	v_add_f32_e32 v115, v186, v187
	s_waitcnt vmcnt(11)
	v_cvt_pk_f32_fp8_e32 v[168:169], v16
	v_cvt_pk_f32_fp8_sdwa v[170:171], v16 src0_sel:WORD_1
	v_cvt_pk_f32_fp8_e32 v[172:173], v17
	v_cvt_pk_f32_fp8_sdwa v[174:175], v17 src0_sel:WORD_1
	v_cvt_pk_f32_fp8_e32 v[176:177], v18
	v_cvt_pk_f32_fp8_sdwa v[178:179], v18 src0_sel:WORD_1
	v_cvt_pk_f32_fp8_e32 v[180:181], v19
	v_cvt_pk_f32_fp8_sdwa v[182:183], v19 src0_sel:WORD_1
	s_waitcnt vmcnt(10)
	v_cvt_pk_f32_fp8_e32 v[96:97], v20
	v_cvt_pk_f32_fp8_sdwa v[98:99], v20 src0_sel:WORD_1
	v_cvt_pk_f32_fp8_e32 v[100:101], v21
	v_cvt_pk_f32_fp8_sdwa v[102:103], v21 src0_sel:WORD_1
	v_cvt_pk_f32_fp8_e32 v[104:105], v22
	v_cvt_pk_f32_fp8_sdwa v[106:107], v22 src0_sel:WORD_1
	v_cvt_pk_f32_fp8_e32 v[108:109], v23
	v_cvt_pk_f32_fp8_sdwa v[110:111], v23 src0_sel:WORD_1
	v_pk_mul_f32 v[184:185], v[168:169], v[80:81]
	v_pk_mul_f32 v[186:187], v[96:97], v[80:81]
	v_pk_fma_f32 v[184:185], v[170:171], v[82:83], v[184:185]
	v_pk_fma_f32 v[186:187], v[98:99], v[82:83], v[186:187]
	v_pk_fma_f32 v[184:185], v[172:173], v[84:85], v[184:185]
	v_pk_fma_f32 v[186:187], v[100:101], v[84:85], v[186:187]
	v_pk_fma_f32 v[184:185], v[174:175], v[86:87], v[184:185]
	v_pk_fma_f32 v[186:187], v[102:103], v[86:87], v[186:187]
	v_pk_fma_f32 v[184:185], v[176:177], v[88:89], v[184:185]
	v_pk_fma_f32 v[186:187], v[104:105], v[88:89], v[186:187]
	v_pk_fma_f32 v[184:185], v[178:179], v[90:91], v[184:185]
	v_pk_fma_f32 v[186:187], v[106:107], v[90:91], v[186:187]
	v_pk_fma_f32 v[184:185], v[180:181], v[92:93], v[184:185]
	v_pk_fma_f32 v[186:187], v[108:109], v[92:93], v[186:187]
	v_pk_fma_f32 v[184:185], v[182:183], v[94:95], v[184:185]
	v_pk_fma_f32 v[186:187], v[110:111], v[94:95], v[186:187]
	v_add_f32_e32 v116, v184, v185
	v_add_f32_e32 v117, v186, v187
	s_waitcnt vmcnt(9)
	v_cvt_pk_f32_fp8_e32 v[168:169], v24
	v_cvt_pk_f32_fp8_sdwa v[170:171], v24 src0_sel:WORD_1
	v_cvt_pk_f32_fp8_e32 v[172:173], v25
	v_cvt_pk_f32_fp8_sdwa v[174:175], v25 src0_sel:WORD_1
	v_cvt_pk_f32_fp8_e32 v[176:177], v26
	v_cvt_pk_f32_fp8_sdwa v[178:179], v26 src0_sel:WORD_1
	v_cvt_pk_f32_fp8_e32 v[180:181], v27
	v_cvt_pk_f32_fp8_sdwa v[182:183], v27 src0_sel:WORD_1
	s_waitcnt vmcnt(8)
	v_cvt_pk_f32_fp8_e32 v[96:97], v28
	v_cvt_pk_f32_fp8_sdwa v[98:99], v28 src0_sel:WORD_1
	v_cvt_pk_f32_fp8_e32 v[100:101], v29
	v_cvt_pk_f32_fp8_sdwa v[102:103], v29 src0_sel:WORD_1
	v_cvt_pk_f32_fp8_e32 v[104:105], v30
	v_cvt_pk_f32_fp8_sdwa v[106:107], v30 src0_sel:WORD_1
	v_cvt_pk_f32_fp8_e32 v[108:109], v31
	v_cvt_pk_f32_fp8_sdwa v[110:111], v31 src0_sel:WORD_1
	v_pk_mul_f32 v[184:185], v[168:169], v[80:81]
	v_pk_mul_f32 v[186:187], v[96:97], v[80:81]
	v_pk_fma_f32 v[184:185], v[170:171], v[82:83], v[184:185]
	v_pk_fma_f32 v[186:187], v[98:99], v[82:83], v[186:187]
	v_pk_fma_f32 v[184:185], v[172:173], v[84:85], v[184:185]
	v_pk_fma_f32 v[186:187], v[100:101], v[84:85], v[186:187]
	v_pk_fma_f32 v[184:185], v[174:175], v[86:87], v[184:185]
	v_pk_fma_f32 v[186:187], v[102:103], v[86:87], v[186:187]
	v_pk_fma_f32 v[184:185], v[176:177], v[88:89], v[184:185]
	v_pk_fma_f32 v[186:187], v[104:105], v[88:89], v[186:187]
	v_pk_fma_f32 v[184:185], v[178:179], v[90:91], v[184:185]
	v_pk_fma_f32 v[186:187], v[106:107], v[90:91], v[186:187]
	v_pk_fma_f32 v[184:185], v[180:181], v[92:93], v[184:185]
	v_pk_fma_f32 v[186:187], v[108:109], v[92:93], v[186:187]
	v_pk_fma_f32 v[184:185], v[182:183], v[94:95], v[184:185]
	v_pk_fma_f32 v[186:187], v[110:111], v[94:95], v[186:187]
	v_add_f32_e32 v118, v184, v185
	v_add_f32_e32 v119, v186, v187
	s_waitcnt vmcnt(7)
	v_cvt_pk_f32_fp8_e32 v[168:169], v32
	v_cvt_pk_f32_fp8_sdwa v[170:171], v32 src0_sel:WORD_1
	v_cvt_pk_f32_fp8_e32 v[172:173], v33
	v_cvt_pk_f32_fp8_sdwa v[174:175], v33 src0_sel:WORD_1
	v_cvt_pk_f32_fp8_e32 v[176:177], v34
	v_cvt_pk_f32_fp8_sdwa v[178:179], v34 src0_sel:WORD_1
	v_cvt_pk_f32_fp8_e32 v[180:181], v35
	v_cvt_pk_f32_fp8_sdwa v[182:183], v35 src0_sel:WORD_1
	s_waitcnt vmcnt(6)
	v_cvt_pk_f32_fp8_e32 v[96:97], v36
	v_cvt_pk_f32_fp8_sdwa v[98:99], v36 src0_sel:WORD_1
	v_cvt_pk_f32_fp8_e32 v[100:101], v37
	v_cvt_pk_f32_fp8_sdwa v[102:103], v37 src0_sel:WORD_1
	v_cvt_pk_f32_fp8_e32 v[104:105], v38
	v_cvt_pk_f32_fp8_sdwa v[106:107], v38 src0_sel:WORD_1
	v_cvt_pk_f32_fp8_e32 v[108:109], v39
	v_cvt_pk_f32_fp8_sdwa v[110:111], v39 src0_sel:WORD_1
	v_pk_mul_f32 v[184:185], v[168:169], v[80:81]
	v_pk_mul_f32 v[186:187], v[96:97], v[80:81]
	v_pk_fma_f32 v[184:185], v[170:171], v[82:83], v[184:185]
	v_pk_fma_f32 v[186:187], v[98:99], v[82:83], v[186:187]
	v_pk_fma_f32 v[184:185], v[172:173], v[84:85], v[184:185]
	v_pk_fma_f32 v[186:187], v[100:101], v[84:85], v[186:187]
	v_pk_fma_f32 v[184:185], v[174:175], v[86:87], v[184:185]
	v_pk_fma_f32 v[186:187], v[102:103], v[86:87], v[186:187]
	v_pk_fma_f32 v[184:185], v[176:177], v[88:89], v[184:185]
	v_pk_fma_f32 v[186:187], v[104:105], v[88:89], v[186:187]
	v_pk_fma_f32 v[184:185], v[178:179], v[90:91], v[184:185]
	v_pk_fma_f32 v[186:187], v[106:107], v[90:91], v[186:187]
	v_pk_fma_f32 v[184:185], v[180:181], v[92:93], v[184:185]
	v_pk_fma_f32 v[186:187], v[108:109], v[92:93], v[186:187]
	v_pk_fma_f32 v[184:185], v[182:183], v[94:95], v[184:185]
	v_pk_fma_f32 v[186:187], v[110:111], v[94:95], v[186:187]
	v_add_f32_e32 v120, v184, v185
	v_add_f32_e32 v121, v186, v187
	s_waitcnt vmcnt(5)
	v_cvt_pk_f32_fp8_e32 v[168:169], v40
	v_cvt_pk_f32_fp8_sdwa v[170:171], v40 src0_sel:WORD_1
	v_cvt_pk_f32_fp8_e32 v[172:173], v41
	v_cvt_pk_f32_fp8_sdwa v[174:175], v41 src0_sel:WORD_1
	v_cvt_pk_f32_fp8_e32 v[176:177], v42
	v_cvt_pk_f32_fp8_sdwa v[178:179], v42 src0_sel:WORD_1
	v_cvt_pk_f32_fp8_e32 v[180:181], v43
	v_cvt_pk_f32_fp8_sdwa v[182:183], v43 src0_sel:WORD_1
	s_waitcnt vmcnt(4)
	v_cvt_pk_f32_fp8_e32 v[96:97], v44
	v_cvt_pk_f32_fp8_sdwa v[98:99], v44 src0_sel:WORD_1
	v_cvt_pk_f32_fp8_e32 v[100:101], v45
	v_cvt_pk_f32_fp8_sdwa v[102:103], v45 src0_sel:WORD_1
	v_cvt_pk_f32_fp8_e32 v[104:105], v46
	v_cvt_pk_f32_fp8_sdwa v[106:107], v46 src0_sel:WORD_1
	v_cvt_pk_f32_fp8_e32 v[108:109], v47
	v_cvt_pk_f32_fp8_sdwa v[110:111], v47 src0_sel:WORD_1
	v_pk_mul_f32 v[184:185], v[168:169], v[80:81]
	v_pk_mul_f32 v[186:187], v[96:97], v[80:81]
	v_pk_fma_f32 v[184:185], v[170:171], v[82:83], v[184:185]
	v_pk_fma_f32 v[186:187], v[98:99], v[82:83], v[186:187]
	v_pk_fma_f32 v[184:185], v[172:173], v[84:85], v[184:185]
	v_pk_fma_f32 v[186:187], v[100:101], v[84:85], v[186:187]
	v_pk_fma_f32 v[184:185], v[174:175], v[86:87], v[184:185]
	v_pk_fma_f32 v[186:187], v[102:103], v[86:87], v[186:187]
	v_pk_fma_f32 v[184:185], v[176:177], v[88:89], v[184:185]
	v_pk_fma_f32 v[186:187], v[104:105], v[88:89], v[186:187]
	v_pk_fma_f32 v[184:185], v[178:179], v[90:91], v[184:185]
	v_pk_fma_f32 v[186:187], v[106:107], v[90:91], v[186:187]
	v_pk_fma_f32 v[184:185], v[180:181], v[92:93], v[184:185]
	v_pk_fma_f32 v[186:187], v[108:109], v[92:93], v[186:187]
	v_pk_fma_f32 v[184:185], v[182:183], v[94:95], v[184:185]
	v_pk_fma_f32 v[186:187], v[110:111], v[94:95], v[186:187]
	v_add_f32_e32 v122, v184, v185
	v_add_f32_e32 v123, v186, v187
	s_waitcnt vmcnt(3)
	v_cvt_pk_f32_fp8_e32 v[168:169], v48
	v_cvt_pk_f32_fp8_sdwa v[170:171], v48 src0_sel:WORD_1
	v_cvt_pk_f32_fp8_e32 v[172:173], v49
	v_cvt_pk_f32_fp8_sdwa v[174:175], v49 src0_sel:WORD_1
	v_cvt_pk_f32_fp8_e32 v[176:177], v50
	v_cvt_pk_f32_fp8_sdwa v[178:179], v50 src0_sel:WORD_1
	v_cvt_pk_f32_fp8_e32 v[180:181], v51
	v_cvt_pk_f32_fp8_sdwa v[182:183], v51 src0_sel:WORD_1
	s_waitcnt vmcnt(2)
	v_cvt_pk_f32_fp8_e32 v[96:97], v52
	v_cvt_pk_f32_fp8_sdwa v[98:99], v52 src0_sel:WORD_1
	v_cvt_pk_f32_fp8_e32 v[100:101], v53
	v_cvt_pk_f32_fp8_sdwa v[102:103], v53 src0_sel:WORD_1
	v_cvt_pk_f32_fp8_e32 v[104:105], v54
	v_cvt_pk_f32_fp8_sdwa v[106:107], v54 src0_sel:WORD_1
	v_cvt_pk_f32_fp8_e32 v[108:109], v55
	v_cvt_pk_f32_fp8_sdwa v[110:111], v55 src0_sel:WORD_1
	v_pk_mul_f32 v[184:185], v[168:169], v[80:81]
	v_pk_mul_f32 v[186:187], v[96:97], v[80:81]
	v_pk_fma_f32 v[184:185], v[170:171], v[82:83], v[184:185]
	v_pk_fma_f32 v[186:187], v[98:99], v[82:83], v[186:187]
	v_pk_fma_f32 v[184:185], v[172:173], v[84:85], v[184:185]
	v_pk_fma_f32 v[186:187], v[100:101], v[84:85], v[186:187]
	v_pk_fma_f32 v[184:185], v[174:175], v[86:87], v[184:185]
	v_pk_fma_f32 v[186:187], v[102:103], v[86:87], v[186:187]
	v_pk_fma_f32 v[184:185], v[176:177], v[88:89], v[184:185]
	v_pk_fma_f32 v[186:187], v[104:105], v[88:89], v[186:187]
	v_pk_fma_f32 v[184:185], v[178:179], v[90:91], v[184:185]
	v_pk_fma_f32 v[186:187], v[106:107], v[90:91], v[186:187]
	v_pk_fma_f32 v[184:185], v[180:181], v[92:93], v[184:185]
	v_pk_fma_f32 v[186:187], v[108:109], v[92:93], v[186:187]
	v_pk_fma_f32 v[184:185], v[182:183], v[94:95], v[184:185]
	v_pk_fma_f32 v[186:187], v[110:111], v[94:95], v[186:187]
	v_add_f32_e32 v124, v184, v185
	v_add_f32_e32 v125, v186, v187
	s_waitcnt vmcnt(1)
	v_cvt_pk_f32_fp8_e32 v[168:169], v56
	v_cvt_pk_f32_fp8_sdwa v[170:171], v56 src0_sel:WORD_1
	v_cvt_pk_f32_fp8_e32 v[172:173], v57
	v_cvt_pk_f32_fp8_sdwa v[174:175], v57 src0_sel:WORD_1
	v_cvt_pk_f32_fp8_e32 v[176:177], v58
	v_cvt_pk_f32_fp8_sdwa v[178:179], v58 src0_sel:WORD_1
	v_cvt_pk_f32_fp8_e32 v[180:181], v59
	v_cvt_pk_f32_fp8_sdwa v[182:183], v59 src0_sel:WORD_1
	s_waitcnt vmcnt(0)
	v_cvt_pk_f32_fp8_e32 v[96:97], v60
	v_cvt_pk_f32_fp8_sdwa v[98:99], v60 src0_sel:WORD_1
	v_cvt_pk_f32_fp8_e32 v[100:101], v61
	v_cvt_pk_f32_fp8_sdwa v[102:103], v61 src0_sel:WORD_1
	v_cvt_pk_f32_fp8_e32 v[104:105], v62
	v_cvt_pk_f32_fp8_sdwa v[106:107], v62 src0_sel:WORD_1
	v_cvt_pk_f32_fp8_e32 v[108:109], v63
	v_cvt_pk_f32_fp8_sdwa v[110:111], v63 src0_sel:WORD_1
	v_pk_mul_f32 v[184:185], v[168:169], v[80:81]
	v_pk_mul_f32 v[186:187], v[96:97], v[80:81]
	v_pk_fma_f32 v[184:185], v[170:171], v[82:83], v[184:185]
	v_pk_fma_f32 v[186:187], v[98:99], v[82:83], v[186:187]
	v_pk_fma_f32 v[184:185], v[172:173], v[84:85], v[184:185]
	v_pk_fma_f32 v[186:187], v[100:101], v[84:85], v[186:187]
	v_pk_fma_f32 v[184:185], v[174:175], v[86:87], v[184:185]
	v_pk_fma_f32 v[186:187], v[102:103], v[86:87], v[186:187]
	v_pk_fma_f32 v[184:185], v[176:177], v[88:89], v[184:185]
	v_pk_fma_f32 v[186:187], v[104:105], v[88:89], v[186:187]
	v_pk_fma_f32 v[184:185], v[178:179], v[90:91], v[184:185]
	v_pk_fma_f32 v[186:187], v[106:107], v[90:91], v[186:187]
	v_pk_fma_f32 v[184:185], v[180:181], v[92:93], v[184:185]
	v_pk_fma_f32 v[186:187], v[108:109], v[92:93], v[186:187]
	v_pk_fma_f32 v[184:185], v[182:183], v[94:95], v[184:185]
	v_pk_fma_f32 v[186:187], v[110:111], v[94:95], v[186:187]
	v_add_f32_e32 v126, v184, v185
	v_add_f32_e32 v127, v186, v187
	s_nop 1
	v_add_f32_dpp v160, v112, v112 row_half_mirror row_mask:0xf bank_mask:0x5
	v_add_f32_dpp v160, v113, v113 row_half_mirror row_mask:0xf bank_mask:0xa
	v_add_f32_dpp v161, v114, v114 row_half_mirror row_mask:0xf bank_mask:0x5
	v_add_f32_dpp v161, v115, v115 row_half_mirror row_mask:0xf bank_mask:0xa
	v_add_f32_dpp v162, v116, v116 row_half_mirror row_mask:0xf bank_mask:0x5
	v_add_f32_dpp v162, v117, v117 row_half_mirror row_mask:0xf bank_mask:0xa
	v_add_f32_dpp v163, v118, v118 row_half_mirror row_mask:0xf bank_mask:0x5
	v_add_f32_dpp v163, v119, v119 row_half_mirror row_mask:0xf bank_mask:0xa
	v_add_f32_dpp v164, v120, v120 row_half_mirror row_mask:0xf bank_mask:0x5
	v_add_f32_dpp v164, v121, v121 row_half_mirror row_mask:0xf bank_mask:0xa
	v_add_f32_dpp v165, v122, v122 row_half_mirror row_mask:0xf bank_mask:0x5
	v_add_f32_dpp v165, v123, v123 row_half_mirror row_mask:0xf bank_mask:0xa
	v_add_f32_dpp v166, v124, v124 row_half_mirror row_mask:0xf bank_mask:0x5
	v_add_f32_dpp v166, v125, v125 row_half_mirror row_mask:0xf bank_mask:0xa
	v_add_f32_dpp v167, v126, v126 row_half_mirror row_mask:0xf bank_mask:0x5
	v_add_f32_dpp v167, v127, v127 row_half_mirror row_mask:0xf bank_mask:0xa
	ds_read_b128 v[168:171], v210
	ds_read_b128 v[172:175], v210 offset:16
	s_nop 1
	v_add_f32_dpp v160, v160, v160 quad_perm:[1,0,3,2] row_mask:0xf bank_mask:0xf
	v_add_f32_dpp v161, v161, v161 quad_perm:[1,0,3,2] row_mask:0xf bank_mask:0xf
	v_add_f32_dpp v162, v162, v162 quad_perm:[1,0,3,2] row_mask:0xf bank_mask:0xf
	v_add_f32_dpp v163, v163, v163 quad_perm:[1,0,3,2] row_mask:0xf bank_mask:0xf
	v_add_f32_dpp v164, v164, v164 quad_perm:[1,0,3,2] row_mask:0xf bank_mask:0xf
	v_add_f32_dpp v165, v165, v165 quad_perm:[1,0,3,2] row_mask:0xf bank_mask:0xf
	v_add_f32_dpp v166, v166, v166 quad_perm:[1,0,3,2] row_mask:0xf bank_mask:0xf
	v_add_f32_dpp v167, v167, v167 quad_perm:[1,0,3,2] row_mask:0xf bank_mask:0xf
	s_nop 1
	v_add_f32_dpp v160, v160, v160 quad_perm:[2,3,0,1] row_mask:0xf bank_mask:0xf
	v_add_f32_dpp v161, v161, v161 quad_perm:[2,3,0,1] row_mask:0xf bank_mask:0xf
	v_add_f32_dpp v162, v162, v162 quad_perm:[2,3,0,1] row_mask:0xf bank_mask:0xf
	v_add_f32_dpp v163, v163, v163 quad_perm:[2,3,0,1] row_mask:0xf bank_mask:0xf
	v_add_f32_dpp v164, v164, v164 quad_perm:[2,3,0,1] row_mask:0xf bank_mask:0xf
	v_add_f32_dpp v165, v165, v165 quad_perm:[2,3,0,1] row_mask:0xf bank_mask:0xf
	v_add_f32_dpp v166, v166, v166 quad_perm:[2,3,0,1] row_mask:0xf bank_mask:0xf
	v_add_f32_dpp v167, v167, v167 quad_perm:[2,3,0,1] row_mask:0xf bank_mask:0xf
	s_waitcnt lgkmcnt(0)
	v_fmac_f32_e32 v168, v208, v160
	v_fmac_f32_e32 v169, v208, v161
	v_fmac_f32_e32 v170, v208, v162
	v_fmac_f32_e32 v171, v208, v163
	v_fmac_f32_e32 v172, v208, v164
	v_fmac_f32_e32 v173, v208, v165
	v_fmac_f32_e32 v174, v208, v166
	v_fmac_f32_e32 v175, v208, v167
	ds_write_b128 v210, v[168:171]
	ds_write_b128 v210, v[172:175] offset:16
	s_add_i32 s17, s17, 1
	s_cmp_lt_i32 s17, s43
	s_cbranch_scc1 .Lpb_unit
	s_add_i32 s16, s16, 1
	s_cmp_lt_i32 s16, 8
	s_cbranch_scc1 .Lpb_slice
	v_and_b32_e32 v160, 63, v218
	v_and_b32_e32 v161, 0x30, v160
	v_and_b32_e32 v162, 1, v160
	v_bfe_u32 v163, v160, 1, 3
	v_lshl_add_u32 v161, v162, 3, v161
	v_add_u32_e32 v161, v161, v163
	v_lshlrev_b32_e32 v161, 2, v161
	v_lshlrev_b32_e32 v160, 2, v160
	v_sub_u32_e32 v162, v202, v160
	v_add_u32_e32 v161, v161, v162
	v_add_u32_e32 v161, 0x2400, v161
	s_mov_b32 s17, 0
